# gu supertile: stagger co-resident blocks (bid>=256) by 512 cycles at each round start
# speedup vs baseline: 1.0006x; 1.0006x over previous
; DI void phase_gu(const Params& p, char* wsb, int sub, int mrows, char* lds) {
;   int mt, nt;
;   for (int rnd = 0; next_tile(rnd, 128, 44, mt, nt); ++rnd) gu_tile<2>(wsb, sub, mt * 128, nt * 128, lds);
;   if (mrows > TL)
;     for (int rnd = 0; next_tile(rnd, 32, 44, mt, nt); ++rnd) gu_tile<1>(wsb, sub, TL + mt * 64, nt * 128, lds);
.Lgu1_round:
	s_cmpk_lt_u32 s96, 0x100
	s_cbranch_scc1 .Lgu1_nostag
	s_sleep 8
